# Toeplitz k-loops: dead tap-index counter updates removed (13 VALU per iteration)
# speedup vs baseline: 1.0068x; 1.0068x over previous
.LBB0_565:
	ds_read_b128 v[214:217], v242 offset:4096
	ds_read_b128 v[218:221], v243 offset:4096
	ds_read_b128 v[222:225], v244 offset:4096
	ds_read_b128 v[226:229], v245 offset:4096
	ds_read_b128 v[20:23], v3
	v_add_u32_e32 v3, 64, v3
	v_add_u32_e32 v234, v238, v234
	v_add_u32_e32 v235, v238, v235
	v_add_u32_e32 v236, v238, v236
	v_add_u32_e32 v237, v238, v237
	v_cmp_lt_i32_e64 s[98:99], v234, v91
	v_cmp_lt_i32_e64 s[100:101], v235, v91
	v_cmp_lt_i32_e64 vcc, v236, v91
	v_cndmask_b32_e64 v242, v234, v246, s[98:99]
	v_cmp_lt_i32_e64 s[98:99], v237, v91
	v_cndmask_b32_e64 v243, v235, v246, s[100:101]
	v_cndmask_b32_e64 v244, v236, v246, vcc
	s_nop 0
	v_cndmask_b32_e64 v245, v237, v246, s[98:99]
	s_add_i32 s36, s36, 1
	s_cmp_lt_i32 s36, s33
	s_waitcnt lgkmcnt(0)
	v_mfma_f32_16x16x32_bf16 v[16:19], v[214:217], v[20:23], v[16:19]
	v_mfma_f32_16x16x32_bf16 v[12:15], v[218:221], v[20:23], v[12:15]
	v_mfma_f32_16x16x32_bf16 v[8:11], v[222:225], v[20:23], v[8:11]
	v_mfma_f32_16x16x32_bf16 v[4:7], v[226:229], v[20:23], v[4:7]
	s_cbranch_scc1 .LBB0_565
	s_cmp_eq_u32 s3, 1
	s_cselect_b64 s[44:45], -1, 0
	s_cmp_lg_u32 s3, 1
	s_cbranch_scc1 .LBB0_582

.LBB0_569:
	ds_read_b128 v[214:217], v242 offset:4096
	ds_read_b128 v[218:221], v243 offset:4096
	ds_read_b128 v[222:225], v244 offset:4096
	ds_read_b128 v[226:229], v245 offset:4096
	ds_read_b128 v[36:39], v3
	v_add_u32_e32 v3, 64, v3
	v_add_u32_e32 v234, v238, v234
	v_add_u32_e32 v235, v238, v235
	v_add_u32_e32 v236, v238, v236
	v_add_u32_e32 v237, v238, v237
	v_cmp_lt_i32_e64 s[98:99], v234, v91
	v_cmp_lt_i32_e64 s[100:101], v235, v91
	v_cmp_lt_i32_e64 vcc, v236, v91
	v_cndmask_b32_e64 v242, v234, v246, s[98:99]
	v_cmp_lt_i32_e64 s[98:99], v237, v91
	v_cndmask_b32_e64 v243, v235, v246, s[100:101]
	v_cndmask_b32_e64 v244, v236, v246, vcc
	s_nop 0
	v_cndmask_b32_e64 v245, v237, v246, s[98:99]
	s_add_i32 s36, s36, 1
	s_cmp_lt_i32 s36, s33
	s_waitcnt lgkmcnt(0)
	v_mfma_f32_16x16x32_bf16 v[32:35], v[214:217], v[36:39], v[32:35]
	v_mfma_f32_16x16x32_bf16 v[28:31], v[218:221], v[36:39], v[28:31]
	v_mfma_f32_16x16x32_bf16 v[24:27], v[222:225], v[36:39], v[24:27]
	v_mfma_f32_16x16x32_bf16 v[20:23], v[226:229], v[36:39], v[20:23]
	s_cbranch_scc1 .LBB0_569
	s_branch .LBB0_571

.LBB0_574:
	ds_read_b128 v[214:217], v242 offset:4096
	ds_read_b128 v[218:221], v243 offset:4096
	ds_read_b128 v[222:225], v244 offset:4096
	ds_read_b128 v[226:229], v245 offset:4096
	ds_read_b128 v[68:71], v3
	v_add_u32_e32 v3, 64, v3
	v_add_u32_e32 v234, v238, v234
	v_add_u32_e32 v235, v238, v235
	v_add_u32_e32 v236, v238, v236
	v_add_u32_e32 v237, v238, v237
	v_cmp_lt_i32_e64 s[98:99], v234, v91
	v_cmp_lt_i32_e64 s[100:101], v235, v91
	v_cmp_lt_i32_e64 vcc, v236, v91
	v_cndmask_b32_e64 v242, v234, v246, s[98:99]
	v_cmp_lt_i32_e64 s[98:99], v237, v91
	v_cndmask_b32_e64 v243, v235, v246, s[100:101]
	v_cndmask_b32_e64 v244, v236, v246, vcc
	s_nop 0
	v_cndmask_b32_e64 v245, v237, v246, s[98:99]
	s_add_i32 s36, s36, 1
	s_cmp_lt_i32 s36, s33
	s_waitcnt lgkmcnt(0)
	v_mfma_f32_16x16x32_bf16 v[56:59], v[214:217], v[68:71], v[56:59]
	v_mfma_f32_16x16x32_bf16 v[52:55], v[218:221], v[68:71], v[52:55]
	v_mfma_f32_16x16x32_bf16 v[44:47], v[222:225], v[68:71], v[44:47]
	v_mfma_f32_16x16x32_bf16 v[36:39], v[226:229], v[68:71], v[36:39]
	s_cbranch_scc1 .LBB0_574
	s_branch .LBB0_576

.LBB0_579:
	ds_read_b128 v[214:217], v242 offset:4096
	ds_read_b128 v[218:221], v243 offset:4096
	ds_read_b128 v[222:225], v244 offset:4096
	ds_read_b128 v[226:229], v245 offset:4096
	ds_read_b128 v[84:87], v3
	v_add_u32_e32 v3, 64, v3
	v_add_u32_e32 v234, v238, v234
	v_add_u32_e32 v235, v238, v235
	v_add_u32_e32 v236, v238, v236
	v_add_u32_e32 v237, v238, v237
	v_cmp_lt_i32_e64 s[98:99], v234, v91
	v_cmp_lt_i32_e64 s[100:101], v235, v91
	v_cmp_lt_i32_e64 vcc, v236, v91
	v_cndmask_b32_e64 v242, v234, v246, s[98:99]
	v_cmp_lt_i32_e64 s[98:99], v237, v91
	v_cndmask_b32_e64 v243, v235, v246, s[100:101]
	v_cndmask_b32_e64 v244, v236, v246, vcc
	s_nop 0
	v_cndmask_b32_e64 v245, v237, v246, s[98:99]
	s_add_i32 s33, s33, 1
	s_cmp_lt_i32 s33, s3
	s_waitcnt lgkmcnt(0)
	v_mfma_f32_16x16x32_bf16 v[80:83], v[214:217], v[84:87], v[80:83]
	v_mfma_f32_16x16x32_bf16 v[76:79], v[218:221], v[84:87], v[76:79]
	v_mfma_f32_16x16x32_bf16 v[72:75], v[222:225], v[84:87], v[72:75]
	v_mfma_f32_16x16x32_bf16 v[68:71], v[226:229], v[84:87], v[68:71]
	s_cbranch_scc1 .LBB0_579
	s_branch .LBB0_585

.LBB0_588:
	ds_read_b128 v[214:217], v242 offset:4096
	ds_read_b128 v[218:221], v243 offset:4096
	ds_read_b128 v[222:225], v244 offset:4096
	ds_read_b128 v[226:229], v245 offset:4096
	ds_read_b128 v[40:43], v3
	v_add_u32_e32 v3, 64, v3
	v_add_u32_e32 v234, v238, v234
	v_add_u32_e32 v235, v238, v235
	v_add_u32_e32 v236, v238, v236
	v_add_u32_e32 v237, v238, v237
	v_cmp_lt_i32_e64 s[98:99], v234, v91
	v_cmp_lt_i32_e64 s[100:101], v235, v91
	v_cmp_lt_i32_e64 vcc, v236, v91
	v_cndmask_b32_e64 v242, v234, v246, s[98:99]
	v_cmp_lt_i32_e64 s[98:99], v237, v91
	v_cndmask_b32_e64 v243, v235, v246, s[100:101]
	v_cndmask_b32_e64 v244, v236, v246, vcc
	s_nop 0
	v_cndmask_b32_e64 v245, v237, v246, s[98:99]
	s_add_i32 s33, s33, 1
	s_cmp_lt_i32 s33, s3
	s_waitcnt lgkmcnt(0)
	v_mfma_f32_16x16x32_bf16 v[16:19], v[214:217], v[40:43], v[16:19]
	v_mfma_f32_16x16x32_bf16 v[12:15], v[218:221], v[40:43], v[12:15]
	v_mfma_f32_16x16x32_bf16 v[8:11], v[222:225], v[40:43], v[8:11]
	v_mfma_f32_16x16x32_bf16 v[4:7], v[226:229], v[40:43], v[4:7]
	s_cbranch_scc1 .LBB0_588

.LBB0_592:
	ds_read_b128 v[214:217], v242 offset:4096
	ds_read_b128 v[218:221], v243 offset:4096
	ds_read_b128 v[222:225], v244 offset:4096
	ds_read_b128 v[226:229], v245 offset:4096
	ds_read_b128 v[40:43], v3
	v_add_u32_e32 v3, 64, v3
	v_add_u32_e32 v234, v238, v234
	v_add_u32_e32 v235, v238, v235
	v_add_u32_e32 v236, v238, v236
	v_add_u32_e32 v237, v238, v237
	v_cmp_lt_i32_e64 s[98:99], v234, v91
	v_cmp_lt_i32_e64 s[100:101], v235, v91
	v_cmp_lt_i32_e64 vcc, v236, v91
	v_cndmask_b32_e64 v242, v234, v246, s[98:99]
	v_cmp_lt_i32_e64 s[98:99], v237, v91
	v_cndmask_b32_e64 v243, v235, v246, s[100:101]
	v_cndmask_b32_e64 v244, v236, v246, vcc
	s_nop 0
	v_cndmask_b32_e64 v245, v237, v246, s[98:99]
	s_add_i32 s33, s33, 1
	s_cmp_lt_i32 s33, s3
	s_waitcnt lgkmcnt(0)
	v_mfma_f32_16x16x32_bf16 v[32:35], v[214:217], v[40:43], v[32:35]
	v_mfma_f32_16x16x32_bf16 v[28:31], v[218:221], v[40:43], v[28:31]
	v_mfma_f32_16x16x32_bf16 v[24:27], v[222:225], v[40:43], v[24:27]
	v_mfma_f32_16x16x32_bf16 v[20:23], v[226:229], v[40:43], v[20:23]
	s_cbranch_scc1 .LBB0_592

.LBB0_596:
	ds_read_b128 v[214:217], v242 offset:4096
	ds_read_b128 v[218:221], v243 offset:4096
	ds_read_b128 v[222:225], v244 offset:4096
	ds_read_b128 v[226:229], v245 offset:4096
	ds_read_b128 v[40:43], v3
	v_add_u32_e32 v3, 64, v3
	v_add_u32_e32 v234, v238, v234
	v_add_u32_e32 v235, v238, v235
	v_add_u32_e32 v236, v238, v236
	v_add_u32_e32 v237, v238, v237
	v_cmp_lt_i32_e64 s[98:99], v234, v91
	v_cmp_lt_i32_e64 s[100:101], v235, v91
	v_cmp_lt_i32_e64 vcc, v236, v91
	v_cndmask_b32_e64 v242, v234, v246, s[98:99]
	v_cmp_lt_i32_e64 s[98:99], v237, v91
	v_cndmask_b32_e64 v243, v235, v246, s[100:101]
	v_cndmask_b32_e64 v244, v236, v246, vcc
	s_nop 0
	v_cndmask_b32_e64 v245, v237, v246, s[98:99]
	s_add_i32 s33, s33, 1
	s_cmp_lt_i32 s33, s3
	s_waitcnt lgkmcnt(0)
	v_mfma_f32_16x16x32_bf16 v[56:59], v[214:217], v[40:43], v[56:59]
	v_mfma_f32_16x16x32_bf16 v[52:55], v[218:221], v[40:43], v[52:55]
	v_mfma_f32_16x16x32_bf16 v[44:47], v[222:225], v[40:43], v[44:47]
	v_mfma_f32_16x16x32_bf16 v[36:39], v[226:229], v[40:43], v[36:39]
	s_cbranch_scc1 .LBB0_596

.LBB0_600:
	ds_read_b128 v[214:217], v242 offset:4096
	ds_read_b128 v[218:221], v243 offset:4096
	ds_read_b128 v[222:225], v244 offset:4096
	ds_read_b128 v[226:229], v245 offset:4096
	ds_read_b128 v[40:43], v3
	v_add_u32_e32 v3, 64, v3
	v_add_u32_e32 v234, v238, v234
	v_add_u32_e32 v235, v238, v235
	v_add_u32_e32 v236, v238, v236
	v_add_u32_e32 v237, v238, v237
	v_cmp_lt_i32_e64 s[98:99], v234, v91
	v_cmp_lt_i32_e64 s[100:101], v235, v91
	v_cmp_lt_i32_e64 vcc, v236, v91
	v_cndmask_b32_e64 v242, v234, v246, s[98:99]
	v_cmp_lt_i32_e64 s[98:99], v237, v91
	v_cndmask_b32_e64 v243, v235, v246, s[100:101]
	v_cndmask_b32_e64 v244, v236, v246, vcc
	s_nop 0
	v_cndmask_b32_e64 v245, v237, v246, s[98:99]
	s_add_i32 s3, s3, 1
	s_cmp_lt_i32 s3, s2
	s_waitcnt lgkmcnt(0)
	v_mfma_f32_16x16x32_bf16 v[80:83], v[214:217], v[40:43], v[80:83]
	v_mfma_f32_16x16x32_bf16 v[76:79], v[218:221], v[40:43], v[76:79]
	v_mfma_f32_16x16x32_bf16 v[72:75], v[222:225], v[40:43], v[72:75]
	v_mfma_f32_16x16x32_bf16 v[68:71], v[226:229], v[40:43], v[68:71]
	s_cbranch_scc1 .LBB0_600

.LBB0_721:
	ds_read_b128 v[214:217], v242 offset:4096
	ds_read_b128 v[218:221], v243 offset:4096
	ds_read_b128 v[222:225], v244 offset:4096
	ds_read_b128 v[226:229], v245 offset:4096
	ds_read_b128 v[20:23], v3
	v_add_u32_e32 v3, 64, v3
	v_add_u32_e32 v234, v238, v234
	v_add_u32_e32 v235, v238, v235
	v_add_u32_e32 v236, v238, v236
	v_add_u32_e32 v237, v238, v237
	v_cmp_lt_i32_e64 s[98:99], v234, v89
	v_cmp_lt_i32_e64 s[100:101], v235, v89
	v_cmp_lt_i32_e64 s[38:39], v236, v89
	v_cndmask_b32_e64 v242, v234, v246, s[98:99]
	v_cmp_lt_i32_e64 s[98:99], v237, v89
	v_cndmask_b32_e64 v243, v235, v246, s[100:101]
	v_cndmask_b32_e64 v244, v236, v246, s[38:39]
	s_nop 0
	v_cndmask_b32_e64 v245, v237, v246, s[98:99]
	s_add_i32 s33, s33, 1
	s_cmp_lt_i32 s33, s19
	s_waitcnt lgkmcnt(0)
	v_mfma_f32_16x16x32_bf16 v[16:19], v[214:217], v[20:23], v[16:19]
	v_mfma_f32_16x16x32_bf16 v[12:15], v[218:221], v[20:23], v[12:15]
	v_mfma_f32_16x16x32_bf16 v[8:11], v[222:225], v[20:23], v[8:11]
	v_mfma_f32_16x16x32_bf16 v[4:7], v[226:229], v[20:23], v[4:7]
	s_cbranch_scc1 .LBB0_721
	s_branch .LBB0_723

.LBB0_725:
	ds_read_b128 v[214:217], v242 offset:4096
	ds_read_b128 v[218:221], v243 offset:4096
	ds_read_b128 v[222:225], v244 offset:4096
	ds_read_b128 v[226:229], v245 offset:4096
	ds_read_b128 v[36:39], v3
	v_add_u32_e32 v3, 64, v3
	v_add_u32_e32 v234, v238, v234
	v_add_u32_e32 v235, v238, v235
	v_add_u32_e32 v236, v238, v236
	v_add_u32_e32 v237, v238, v237
	v_cmp_lt_i32_e64 s[98:99], v234, v89
	v_cmp_lt_i32_e64 s[100:101], v235, v89
	v_cmp_lt_i32_e64 s[38:39], v236, v89
	v_cndmask_b32_e64 v242, v234, v246, s[98:99]
	v_cmp_lt_i32_e64 s[98:99], v237, v89
	v_cndmask_b32_e64 v243, v235, v246, s[100:101]
	v_cndmask_b32_e64 v244, v236, v246, s[38:39]
	s_nop 0
	v_cndmask_b32_e64 v245, v237, v246, s[98:99]
	s_add_i32 s37, s37, 1
	s_cmp_lt_i32 s37, s36
	s_waitcnt lgkmcnt(0)
	v_mfma_f32_16x16x32_bf16 v[32:35], v[214:217], v[36:39], v[32:35]
	v_mfma_f32_16x16x32_bf16 v[28:31], v[218:221], v[36:39], v[28:31]
	v_mfma_f32_16x16x32_bf16 v[24:27], v[222:225], v[36:39], v[24:27]
	v_mfma_f32_16x16x32_bf16 v[20:23], v[226:229], v[36:39], v[20:23]
	s_cbranch_scc1 .LBB0_725
	s_branch .LBB0_727

.LBB0_729:
	ds_read_b128 v[214:217], v242 offset:4096
	ds_read_b128 v[218:221], v243 offset:4096
	ds_read_b128 v[222:225], v244 offset:4096
	ds_read_b128 v[226:229], v245 offset:4096
	ds_read_b128 v[68:71], v3
	v_add_u32_e32 v3, 64, v3
	v_add_u32_e32 v234, v238, v234
	v_add_u32_e32 v235, v238, v235
	v_add_u32_e32 v236, v238, v236
	v_add_u32_e32 v237, v238, v237
	v_cmp_lt_i32_e64 s[98:99], v234, v89
	v_cmp_lt_i32_e64 s[100:101], v235, v89
	v_cmp_lt_i32_e64 s[38:39], v236, v89
	v_cndmask_b32_e64 v242, v234, v246, s[98:99]
	v_cmp_lt_i32_e64 s[98:99], v237, v89
	v_cndmask_b32_e64 v243, v235, v246, s[100:101]
	v_cndmask_b32_e64 v244, v236, v246, s[38:39]
	s_nop 0
	v_cndmask_b32_e64 v245, v237, v246, s[98:99]
	s_add_i32 s42, s42, 1
	s_cmp_lt_i32 s42, s40
	s_waitcnt lgkmcnt(0)
	v_mfma_f32_16x16x32_bf16 v[48:51], v[214:217], v[68:71], v[48:51]
	v_mfma_f32_16x16x32_bf16 v[44:47], v[218:221], v[68:71], v[44:47]
	v_mfma_f32_16x16x32_bf16 v[40:43], v[222:225], v[68:71], v[40:43]
	v_mfma_f32_16x16x32_bf16 v[36:39], v[226:229], v[68:71], v[36:39]
	s_cbranch_scc1 .LBB0_729
	s_branch .LBB0_731

.LBB0_733:
	ds_read_b128 v[214:217], v242 offset:4096
	ds_read_b128 v[218:221], v243 offset:4096
	ds_read_b128 v[222:225], v244 offset:4096
	ds_read_b128 v[226:229], v245 offset:4096
	ds_read_b128 v[84:87], v3
	v_add_u32_e32 v3, 64, v3
	v_add_u32_e32 v234, v238, v234
	v_add_u32_e32 v235, v238, v235
	v_add_u32_e32 v236, v238, v236
	v_add_u32_e32 v237, v238, v237
	v_cmp_lt_i32_e64 s[98:99], v234, v89
	v_cmp_lt_i32_e64 s[100:101], v235, v89
	v_cmp_lt_i32_e64 s[38:39], v236, v89
	v_cndmask_b32_e64 v242, v234, v246, s[98:99]
	v_cmp_lt_i32_e64 s[98:99], v237, v89
	v_cndmask_b32_e64 v243, v235, v246, s[100:101]
	v_cndmask_b32_e64 v244, v236, v246, s[38:39]
	s_nop 0
	v_cndmask_b32_e64 v245, v237, v246, s[98:99]
	s_add_i32 s43, s43, 1
	s_cmp_lt_i32 s43, s42
	s_waitcnt lgkmcnt(0)
	v_mfma_f32_16x16x32_bf16 v[80:83], v[214:217], v[84:87], v[80:83]
	v_mfma_f32_16x16x32_bf16 v[76:79], v[218:221], v[84:87], v[76:79]
	v_mfma_f32_16x16x32_bf16 v[72:75], v[222:225], v[84:87], v[72:75]
	v_mfma_f32_16x16x32_bf16 v[68:71], v[226:229], v[84:87], v[68:71]
	s_cbranch_scc1 .LBB0_733
	s_branch .LBB0_735

.LBB0_737:
	ds_read_b128 v[214:217], v242 offset:4096
	ds_read_b128 v[218:221], v243 offset:4096
	ds_read_b128 v[222:225], v244 offset:4096
	ds_read_b128 v[226:229], v245 offset:4096
	ds_read_b128 v[52:55], v3
	v_add_u32_e32 v3, 64, v3
	v_add_u32_e32 v234, v238, v234
	v_add_u32_e32 v235, v238, v235
	v_add_u32_e32 v236, v238, v236
	v_add_u32_e32 v237, v238, v237
	v_cmp_lt_i32_e64 s[98:99], v234, v89
	v_cmp_lt_i32_e64 s[100:101], v235, v89
	v_cmp_lt_i32_e64 s[38:39], v236, v89
	v_cndmask_b32_e64 v242, v234, v246, s[98:99]
	v_cmp_lt_i32_e64 s[98:99], v237, v89
	v_cndmask_b32_e64 v243, v235, v246, s[100:101]
	v_cndmask_b32_e64 v244, v236, v246, s[38:39]
	s_nop 0
	v_cndmask_b32_e64 v245, v237, v246, s[98:99]
	s_add_i32 s3, s3, 1
	s_cmp_lt_i32 s3, s2
	s_waitcnt lgkmcnt(0)
	v_mfma_f32_16x16x32_bf16 v[16:19], v[214:217], v[52:55], v[16:19]
	v_mfma_f32_16x16x32_bf16 v[12:15], v[218:221], v[52:55], v[12:15]
	v_mfma_f32_16x16x32_bf16 v[8:11], v[222:225], v[52:55], v[8:11]
	v_mfma_f32_16x16x32_bf16 v[4:7], v[226:229], v[52:55], v[4:7]
	s_cbranch_scc1 .LBB0_737

.LBB0_740:
	ds_read_b128 v[214:217], v242 offset:4096
	ds_read_b128 v[218:221], v243 offset:4096
	ds_read_b128 v[222:225], v244 offset:4096
	ds_read_b128 v[226:229], v245 offset:4096
	ds_read_b128 v[52:55], v3
	v_add_u32_e32 v3, 64, v3
	v_add_u32_e32 v234, v238, v234
	v_add_u32_e32 v235, v238, v235
	v_add_u32_e32 v236, v238, v236
	v_add_u32_e32 v237, v238, v237
	v_cmp_lt_i32_e64 s[98:99], v234, v89
	v_cmp_lt_i32_e64 s[100:101], v235, v89
	v_cmp_lt_i32_e64 s[38:39], v236, v89
	v_cndmask_b32_e64 v242, v234, v246, s[98:99]
	v_cmp_lt_i32_e64 s[98:99], v237, v89
	v_cndmask_b32_e64 v243, v235, v246, s[100:101]
	v_cndmask_b32_e64 v244, v236, v246, s[38:39]
	s_nop 0
	v_cndmask_b32_e64 v245, v237, v246, s[98:99]
	s_add_i32 s3, s3, 1
	s_cmp_lt_i32 s3, s2
	s_waitcnt lgkmcnt(0)
	v_mfma_f32_16x16x32_bf16 v[32:35], v[214:217], v[52:55], v[32:35]
	v_mfma_f32_16x16x32_bf16 v[28:31], v[218:221], v[52:55], v[28:31]
	v_mfma_f32_16x16x32_bf16 v[24:27], v[222:225], v[52:55], v[24:27]
	v_mfma_f32_16x16x32_bf16 v[20:23], v[226:229], v[52:55], v[20:23]
	s_cbranch_scc1 .LBB0_740

.LBB0_743:
	ds_read_b128 v[214:217], v242 offset:4096
	ds_read_b128 v[218:221], v243 offset:4096
	ds_read_b128 v[222:225], v244 offset:4096
	ds_read_b128 v[226:229], v245 offset:4096
	ds_read_b128 v[52:55], v3
	v_add_u32_e32 v3, 64, v3
	v_add_u32_e32 v234, v238, v234
	v_add_u32_e32 v235, v238, v235
	v_add_u32_e32 v236, v238, v236
	v_add_u32_e32 v237, v238, v237
	v_cmp_lt_i32_e64 s[98:99], v234, v89
	v_cmp_lt_i32_e64 s[100:101], v235, v89
	v_cmp_lt_i32_e64 s[38:39], v236, v89
	v_cndmask_b32_e64 v242, v234, v246, s[98:99]
	v_cmp_lt_i32_e64 s[98:99], v237, v89
	v_cndmask_b32_e64 v243, v235, v246, s[100:101]
	v_cndmask_b32_e64 v244, v236, v246, s[38:39]
	s_nop 0
	v_cndmask_b32_e64 v245, v237, v246, s[98:99]
	s_add_i32 s3, s3, 1
	s_cmp_lt_i32 s3, s2
	s_waitcnt lgkmcnt(0)
	v_mfma_f32_16x16x32_bf16 v[48:51], v[214:217], v[52:55], v[48:51]
	v_mfma_f32_16x16x32_bf16 v[44:47], v[218:221], v[52:55], v[44:47]
	v_mfma_f32_16x16x32_bf16 v[40:43], v[222:225], v[52:55], v[40:43]
	v_mfma_f32_16x16x32_bf16 v[36:39], v[226:229], v[52:55], v[36:39]
	s_cbranch_scc1 .LBB0_743

.LBB0_746:
	ds_read_b128 v[214:217], v242 offset:4096
	ds_read_b128 v[218:221], v243 offset:4096
	ds_read_b128 v[222:225], v244 offset:4096
	ds_read_b128 v[226:229], v245 offset:4096
	ds_read_b128 v[84:87], v91
	v_add_u32_e32 v91, 64, v91
	v_add_u32_e32 v234, v238, v234
	v_add_u32_e32 v235, v238, v235
	v_add_u32_e32 v236, v238, v236
	v_add_u32_e32 v237, v238, v237
	v_cmp_lt_i32_e64 s[98:99], v234, v89
	v_cmp_lt_i32_e64 s[100:101], v235, v89
	v_cmp_lt_i32_e64 s[38:39], v236, v89
	v_cndmask_b32_e64 v242, v234, v246, s[98:99]
	v_cmp_lt_i32_e64 s[98:99], v237, v89
	v_cndmask_b32_e64 v243, v235, v246, s[100:101]
	v_cndmask_b32_e64 v244, v236, v246, s[38:39]
	s_nop 0
	v_cndmask_b32_e64 v245, v237, v246, s[98:99]
	s_add_i32 s3, s3, 1
	s_cmp_lt_i32 s3, s2
	s_waitcnt lgkmcnt(0)
	v_mfma_f32_16x16x32_bf16 v[64:67], v[214:217], v[84:87], v[64:67]
	v_mfma_f32_16x16x32_bf16 v[60:63], v[218:221], v[84:87], v[60:63]
	v_mfma_f32_16x16x32_bf16 v[56:59], v[222:225], v[84:87], v[56:59]
	v_mfma_f32_16x16x32_bf16 v[52:55], v[226:229], v[84:87], v[52:55]
	s_cbranch_scc1 .LBB0_746
	s_mov_b64 s[38:39], 0
